# MoBA unit schedule: own-block index o = (u&15) xor m[jj] so every CU gets a balanced mix of light and heavy blocks (was x / 15-x alternation)
# speedup vs baseline: 1.0222x; 1.0133x over previous
.LBB0_1873:
	s_and_b32 s19, s90, 15
	s_lshr_b32 s93, s84, 6
	s_lshl_b32 s18, s89, 2
	s_lshr_b32 s20, 0xeda97430, s18
	s_and_b32 s20, s20, 15
	s_xor_b32 s92, s19, s20
	s_ashr_i32 s74, s90, 8
	s_ashr_i32 s75, s74, 31
	s_lshl_b64 s[72:73], s[74:75], 12
	s_lshl_b32 s91, s92, 8
	s_or_b32 s70, s72, s91
	s_mov_b32 s71, s73
	v_lshl_add_u64 v[2:3], s[70:71], 0, v[170:171]
	s_lshl_b32 s18, s90, 2
	v_lshlrev_b64 v[2:3], 11, v[2:3]
	s_and_b32 s94, s18, 0x3c0
	v_lshl_add_u64 v[2:3], s[36:37], 0, v[2:3]
	s_lshl_b32 s50, s94, 1
	v_lshl_add_u64 v[2:3], v[2:3], 0, s[50:51]
	v_mov_b32_e32 v179, v167
	s_cmp_lg_u32 s92, 0
	s_cselect_b64 s[76:77], -1, 0
	s_cmp_eq_u32 s92, 0
	v_lshl_add_u64 v[182:183], v[2:3], 0, v[178:179]
	s_cbranch_scc1 .LBB0_1884
	global_load_dwordx4 v[4:7], v[182:183], off
	global_load_dwordx4 v[8:11], v[182:183], off offset:32
	global_load_dwordx4 v[56:59], v[182:183], off offset:64
	global_load_dwordx4 v[60:63], v[182:183], off offset:96
	s_and_b32 s19, s93, 15
	s_lshl_b32 s18, s74, 4
	s_lshl_b32 s20, s19, 8
	s_ashr_i32 s19, s18, 31
	s_lshl_b64 s[18:19], s[18:19], 12
	s_or_b32 s18, s18, s20
	s_add_u32 s20, s18, 0x300000
	s_addc_u32 s21, s19, 0
	s_add_u32 s20, s20, s56
	s_addc_u32 s21, s21, s57
	s_cmp_lt_u32 s82, 4
	s_cbranch_scc0 .Lkm_noload
	v_lshrrev_b32_e32 v68, 4, v196
	v_and_b32_e32 v69, 15, v196
	v_lshlrev_b32_e32 v68, 12, v68
	v_lshl_or_b32 v68, v69, 4, v68
	global_load_dwordx4 v[64:67], v68, s[20:21]
